# windowed-attention tile loops: V^T row-group loads use a running 64-bit pointer with an SGPR-pair step
# baseline (speedup 1.0000x reference)
; DI int ltid() { int t = threadIdx.x & 255; asm volatile("" : "+v"(t)); return t; }
; template <int MODE>
; DI void attn64_wave(const Params& p, int layer, int b, int hq, int qrow0, int t0, const float* rpb_lds, unsigned char* wlds) {
;   constexpr bool isC = (MODE == 0 || MODE == 2);
;   const int lane = ltid() & 63, qi = lane & 31, hh = lane >> 5;
;   const int pr = (qi & 19) | ((qi & 4) << 1) | ((qi & 8) >> 1);
;   const float* gqp = (isC ? p.na_q_gain : p.sw_q_gain) + layer * 64;
;   const float* gkp = (isC ? p.na_k_gain : p.sw_k_gain) + layer * 64;
;   const float gq = wave_max(fabsf(gqp[lane])), gk = wave_max(fabsf(gkp[lane]));
;   const float negM2 = -(0.125f * LOG2E * 64.f * 1.02f) * gq * gk;
;   const int kvh = isC ? hq : (hq >> 1);
;   const int qcol = isC ? 2048 + 64 * hq : 2816 + 64 * hq;
;   const int kcol = isC ? 2304 + 64 * hq : 3072 + 64 * kvh;
;   const bf16_t* vt = isC ? p.VtC + (size_t)(b * 4 + hq) * 64 * UA : p.VtD + (size_t)(b * 2 + kvh) * 64 * UA;
;   const bf16_t* qp = p.P + (size_t)(qrow0 + qi) * NP + qcol + 8 * hh;
;   bf16x8 qf[4];
; #pragma unroll
;   for (int ks = 0; ks < 4; ++ks) qf[ks] = *(const bf16x8*)(qp + ks * 16);
;   f32x16 o[2];
; #pragma unroll
;   for (int dh = 0; dh < 2; ++dh)
; #pragma unroll
;     for (int i = 0; i < 16; ++i) o[dh][i] = 0.f;
;   float ls = 0.f;
;   constexpr int NT = MODE == 0 ? 24 : (MODE == 1 ? 18 : 8);
;   const int r = t0 >> 6, c = (t0 & 63) + qi;
;   const int rs = min(max(r - 4, 0), 248), ws = min(max(c - 8, 0), 48);
;   const float* rpb = rpb_lds + hq * 465;
;   const int qt = t0 + qi;
.LBB0_337:
	s_nop 3
	v_mov_b32_e32 v2, v212
	v_readlane_b32 s0, v255, 0
	v_and_b32_e32 v6, 63, v2
	v_lshlrev_b32_e32 v0, 2, v6
	v_readlane_b32 s1, v255, 1
	v_cmp_lt_i32_e32 vcc, v218, v217
	s_sub_i32 s2, s40, s48
	s_bfe_u32 s3, s2, 0x20007
	v_cndmask_b32_e32 v7, v216, v218, vcc
	v_cmp_lt_i32_e32 vcc, v219, v217
	global_load_dword v4, v0, s[0:1]
	v_readlane_b32 s0, v255, 2
	v_readlane_b32 s1, v255, 3
	v_cndmask_b32_e32 v8, v216, v219, vcc
	v_cmp_lt_i32_e32 vcc, v220, v217
	s_ashr_i32 s26, s2, 9
	s_lshl_b32 s2, s2, 7
	v_cndmask_b32_e32 v9, v216, v220, vcc
	global_load_dword v5, v0, s[0:1]
	v_cmp_lt_i32_e32 vcc, v221, v217
	s_and_b32 s2, s2, 0x3f80
	v_lshlrev_b32_e32 v13, 1, v2
	v_cndmask_b32_e32 v10, v216, v221, vcc
	v_cmp_lt_i32_e32 vcc, v222, v217
	v_lshrrev_b32_e32 v14, 1, v2
	s_lshl_b32 s27, s26, 14
	v_cndmask_b32_e32 v11, v216, v222, vcc
	v_cmp_lt_i32_e32 vcc, v223, v217
	v_and_b32_e32 v15, 19, v2
	v_lshlrev_b32_e32 v16, 4, v2
	v_cndmask_b32_e32 v12, v216, v223, vcc
	v_add_u32_e32 v18, s2, v152
	v_and_b32_e32 v13, 8, v13
	v_and_b32_e32 v14, 4, v14
	v_lshlrev_b32_e32 v133, 2, v7
	v_lshlrev_b32_e32 v7, 2, v8
	v_lshlrev_b32_e32 v8, 2, v9
	v_lshlrev_b32_e32 v9, 2, v10
	v_lshlrev_b32_e32 v10, 2, v11
	v_lshlrev_b32_e32 v11, 2, v12
	v_and_b32_e32 v12, 31, v2
	v_bfe_u32 v155, v2, 5, 1
	v_bfe_u32 v134, v2, 3, 3
	v_bfe_u32 v17, v2, 2, 4
	v_and_b32_e32 v2, 0x70, v16
	v_add_u32_e32 v16, s27, v18
	v_or3_b32 v13, v15, v13, v14
	v_ashrrev_i32_e32 v14, 6, v18
	v_or_b32_e32 v144, v12, v16
	v_max_i32_e32 v16, 4, v14
	v_add_u32_e32 v16, -4, v16
	v_min_u32_e32 v136, 0xf8, v16
	s_lshl_b32 s22, s3, 6
	v_mov_b64_e32 v[0:1], s[78:79]
	s_lshl_b32 s24, s26, 2
	v_writelane_b32 v255, s22, 10
	s_or_b32 s2, s24, s3
	v_mad_i64_i32 v[0:1], s[24:25], v144, s20, v[0:1]
	v_writelane_b32 v255, s23, 11
	s_lshl_b32 s22, s3, 7
	v_lshlrev_b32_e32 v192, 4, v155
	v_lshl_add_u64 v[0:1], v[0:1], 0, s[22:23]
	v_lshl_add_u64 v[0:1], v[0:1], 0, v[192:193]
	s_mul_i32 s28, s3, 0x744
	s_mul_hi_i32 s3, s2, 0x208000
	s_mul_i32 s2, s2, 0x208000
	s_add_u32 s2, s84, s2
	s_addc_u32 s3, s85, s3
	s_add_i32 s28, s90, s28
	s_add_u32 s24, s78, s22
	v_mov_b32_e32 v3, v193
	s_addc_u32 s25, s79, 0
	s_lshl_b32 s42, s26, 8
	v_lshl_add_u64 v[2:3], s[24:25], 0, v[2:3]
	s_mov_b64 s[0:1], 0x1200
	s_add_i32 s42, s42, 0x8000
	v_lshl_add_u64 v[128:129], v[2:3], 0, s[0:1]
	v_or_b32_e32 v19, v12, v154
	v_sub_u32_e64 v15, v19, 8 clamp
	v_lshlrev_b32_e32 v135, 3, v155
	v_min_u32_e32 v15, 48, v15
	v_cmp_ge_u32_e64 s[0:1], v135, v15
	v_add_u32_e32 v48, 16, v15
	s_add_i32 s22, s27, 0xffffff00
	v_writelane_b32 v255, s0, 12
	v_or_b32_e32 v49, 50, v135
	v_or_b32_e32 v50, 51, v135
	v_writelane_b32 v255, s1, 13
	v_or_b32_e32 v51, 52, v135
	s_waitcnt vmcnt(1)
	v_and_b32_e32 v18, 0x7fffffff, v4
	ds_bpermute_b32 v18, v133, v18
	v_max_f32_e64 v4, |v4|, |v4|
	v_or_b32_e32 v52, 53, v135
	v_or_b32_e32 v53, 54, v135
	v_or_b32_e32 v54, 55, v135
	s_waitcnt lgkmcnt(0)
	v_max_f32_e32 v18, v18, v18
	v_max_f32_e32 v4, v4, v18
	s_waitcnt vmcnt(0)
	v_and_b32_e32 v20, 0x7fffffff, v5
	ds_bpermute_b32 v20, v133, v20
	v_max_f32_e64 v5, |v5|, |v5|
	ds_bpermute_b32 v18, v7, v4
	v_mov_b32_e32 v138, 0
	s_mov_b32 s43, 0
	s_waitcnt lgkmcnt(1)
	v_max_f32_e32 v20, v20, v20
	v_max_f32_e32 v5, v5, v20
	ds_bpermute_b32 v7, v7, v5
	s_waitcnt lgkmcnt(1)
	v_max_f32_e32 v16, v18, v18
	v_max_f32_e32 v16, v4, v16
	ds_bpermute_b32 v18, v8, v16
	s_mov_b32 s41, 32
	s_waitcnt lgkmcnt(1)
	v_max_f32_e32 v7, v7, v7
	v_max_f32_e32 v7, v5, v7
	ds_bpermute_b32 v8, v8, v7
	s_waitcnt lgkmcnt(1)
	v_max_f32_e32 v18, v18, v18
	v_max_f32_e32 v16, v16, v18
	v_lshl_add_u64 v[4:5], v[0:1], 0, s[66:67]
	v_add_co_u32_e32 v0, vcc, s63, v0
	s_waitcnt lgkmcnt(0)
	v_max_f32_e32 v8, v8, v8
	v_max_f32_e32 v7, v7, v8
	ds_bpermute_b32 v8, v9, v16
	ds_bpermute_b32 v9, v9, v7
	v_addc_co_u32_e32 v1, vcc, 0, v1, vcc
	global_load_dwordx4 v[64:67], v[4:5], off offset:32
	global_load_dwordx4 v[68:71], v[4:5], off offset:64
	s_waitcnt lgkmcnt(1)
	v_max_f32_e32 v8, v8, v8
	s_waitcnt lgkmcnt(0)
	v_max_f32_e32 v9, v9, v9
	v_max_f32_e32 v8, v16, v8
	v_max_f32_e32 v7, v7, v9
	ds_bpermute_b32 v9, v10, v8
	ds_bpermute_b32 v10, v10, v7
	global_load_dwordx4 v[72:75], v[0:1], off
	global_load_dwordx4 v[76:79], v[4:5], off offset:96
	v_ashrrev_i32_e32 v145, 31, v144
	s_mov_b32 s89, 0x82000
	s_waitcnt lgkmcnt(1)
	v_max_f32_e32 v9, v9, v9
	s_waitcnt lgkmcnt(0)
	v_max_f32_e32 v10, v10, v10
	v_max_f32_e32 v8, v8, v9
	v_max_f32_e32 v7, v7, v10
	ds_bpermute_b32 v9, v11, v8
	ds_bpermute_b32 v10, v11, v7
	s_mov_b32 s48, 0x104000
	s_mov_b32 s49, 0x186000
	v_sub_u32_e32 v137, v136, v14
	s_waitcnt lgkmcnt(1)
	v_max_f32_e32 v0, v9, v9
	s_waitcnt lgkmcnt(0)
; DI void frag64_load(Frag64& f, const bf16_t* P, const bf16_t* vt, int b, int u, int kcol, int lane) {
; #pragma unroll
;   for (int i = 0; i < 4; ++i) {
;     f.k[i] = *(const u32x4*)(P + (size_t)rowOfU(b, u + (lane >> 3) + 8 * i) * NP + kcol + (lane & 7) * 8);
;     f.v[i] = *(const u32x4*)(vt + (size_t)((lane >> 2) + 16 * i) * UA + u + (lane & 3) * 8);
;   }
; }
; template <int MODE>
; DI void attn64_wave(const Params& p, int layer, int b, int hq, int qrow0, int t0, const float* rpb_lds, unsigned char* wlds) {
;     ...
;   f32x16 o[2];
; #pragma unroll
;   for (int dh = 0; dh < 2; ++dh)
; #pragma unroll
;     for (int i = 0; i < 16; ++i) o[dh][i] = 0.f;
;   float ls = 0.f;
;   constexpr int NT = MODE == 0 ? 24 : (MODE == 1 ? 18 : 8);
;   const int r = t0 >> 6, c = (t0 & 63) + qi;
;   const int rs = min(max(r - 4, 0), 248), ws = min(max(c - 8, 0), 48);
;   const float* rpb = rpb_lds + hq * 465;
;   const int qt = t0 + qi;
;   auto tile_u = [&](int t) -> int {
;     if (t < 8) return 32 * t;
;     if (MODE == 0) return CTX + (rs + ((t - 8) >> 1)) * 64 + ((t - 8) & 1) * 32;
;     const int kt0 = t0 - 128 + 32 * (t - 8);
;     return CTX + min(max(kt0, 0), SEQ - 32);
;   };
;   auto load_tile = [&](Frag64& f, int t) { frag64_load(f, p.P, vt, b, tile_u(t), kcol, lane); };
;   unsigned char* Kw = wlds; unsigned char* Vw = wlds + W64_KB;
;   auto compute_tile = [&](const Frag64& f, int t) {
; #pragma unroll
;     for (int i = 0; i < 4; ++i) {
;       *(u32x4*)(Kw + ((lane >> 3) + 8 * i) * LDS_STRIDE + (lane & 7) * 16) = f.k[i];
;       *(u32x4*)(Vw + ((lane >> 2) + 16 * i) * W64_VSTR + (lane & 3) * 16) = f.v[i];
;     }
;     bf16x8 kf[4], vf[2][2];
; #pragma unroll
;     for (int ks = 0; ks < 4; ++ks) kf[ks] = __builtin_bit_cast(bf16x8, *(const u32x4*)(Kw + pr * LDS_STRIDE + (16 * ks + 8 * hh) * 2));
; #pragma unroll
;     for (int dh = 0; dh < 2; ++dh)
; #pragma unroll
;       for (int s2 = 0; s2 < 2; ++s2) vf[dh][s2] = __builtin_bit_cast(bf16x8, *(const u32x4*)(Vw + (32 * dh + qi) * W64_VSTR + (16 * s2 + 8 * hh) * 2));
;     f32x16 s;
; #pragma unroll
;     for (int i = 0; i < 16; ++i) s[i] = negM2;
; #pragma unroll
;     for (int ks = 0; ks < 4; ++ks) s = MFMA32(kf[ks], qf[ks], s);
;     float pe[16];
;     if (t < 8) {
; #pragma unroll
;       for (int i = 0; i < 16; ++i) pe[i] = fexp2(s[i]);
;     } else if (MODE == 0) {
	v_max_f32_e32 v1, v10, v10
	v_max_f32_e32 v0, v8, v0
	v_max_f32_e32 v1, v7, v1
	v_mul_f32_e32 v0, 0xc13c5bb7, v0
	v_lshlrev_b32_e32 v8, 4, v6
	v_mul_f32_e32 v32, v0, v1
	v_and_b32_e32 v0, 48, v8
	v_mov_b32_e32 v1, v193
	v_lshl_add_u64 v[2:3], s[2:3], 0, v[0:1]
	v_or_b32_e32 v1, s42, v134
	v_mul_u32_u24_e32 v6, 0x8200, v17
	v_mov_b32_e32 v7, v193
	v_lshl_add_u64 v[130:131], v[2:3], 0, v[6:7]
	v_or_b32_e32 v2, 8, v1
	v_mad_u64_u32 v[4:5], s[2:3], v1, s20, v[128:129]
	v_mad_u64_u32 v[2:3], s[2:3], v2, s20, v[128:129]
	global_load_dwordx4 v[80:83], v[130:131], off
	global_load_dwordx4 v[84:87], v[4:5], off
	global_load_dwordx4 v[88:91], v[2:3], off
	v_add_co_u32_e32 v2, vcc, s61, v130
	v_or_b32_e32 v6, 1, v135
	s_nop 0
	v_addc_co_u32_e32 v3, vcc, 0, v131, vcc
	global_load_dwordx4 v[92:95], v[2:3], off
	v_or_b32_e32 v2, 16, v1
	v_mad_u64_u32 v[2:3], s[2:3], v2, s20, v[128:129]
	global_load_dwordx4 v[96:99], v[2:3], off
	v_add_co_u32_e32 v2, vcc, s62, v130
	v_or_b32_e32 v1, 24, v1
	s_nop 0
	v_addc_co_u32_e32 v3, vcc, 0, v131, vcc
	global_load_dwordx4 v[100:103], v[2:3], off
	v_mad_u64_u32 v[2:3], s[2:3], v1, s20, v[128:129]
	global_load_dwordx4 v[104:107], v[2:3], off
	v_add_co_u32_e32 v2, vcc, s64, v130
	v_cmp_ge_u32_e64 s[0:1], v6, v15
	s_nop 0
	v_addc_co_u32_e32 v3, vcc, 0, v131, vcc
	global_load_dwordx4 v[108:111], v[2:3], off
	v_writelane_b32 v255, s0, 14
	v_or_b32_e32 v6, 2, v135
	v_cmp_lt_u32_e32 vcc, v135, v15
	v_writelane_b32 v255, s1, 15
	v_cmp_ge_u32_e64 s[0:1], v6, v15
	v_or_b32_e32 v6, 3, v135
	v_mad_u32_u24 v1, v134, s59, v153
	v_writelane_b32 v255, s0, 16
	v_and_b32_e32 v2, 0x70, v8
	v_mad_u32_u24 v3, v17, s60, v153
	v_writelane_b32 v255, s1, 17
	v_cmp_ge_u32_e64 s[0:1], v6, v15
	v_or_b32_e32 v6, 4, v135
	v_mad_u32_u24 v4, v13, s59, v153
	v_writelane_b32 v255, s0, 18
	v_mad_u32_u24 v5, v12, s60, v153
	v_mov_b32_e32 v33, v32
	v_writelane_b32 v255, s1, 19
	v_cmp_ge_u32_e64 s[0:1], v6, v15
	v_or_b32_e32 v6, 5, v135
	v_mov_b32_e32 v34, v32
	v_writelane_b32 v255, s0, 20
	v_mov_b32_e32 v35, v32
	v_mov_b32_e32 v36, v32
	v_writelane_b32 v255, s1, 21
	v_cmp_ge_u32_e64 s[0:1], v6, v15
	v_or_b32_e32 v6, 6, v135
	v_cmp_ge_u32_e64 s[50:51], v6, v15
	v_or_b32_e32 v6, 7, v135
	v_cmp_ge_u32_e64 s[52:53], v6, v15
	v_or_b32_e32 v6, 16, v135
	v_cmp_ge_u32_e64 s[2:3], v6, v15
	v_or_b32_e32 v6, 17, v135
	v_writelane_b32 v255, s0, 22
	s_and_b64 s[46:47], s[2:3], vcc
	v_cmp_ge_u32_e32 vcc, v6, v15
	v_cmp_lt_u32_e64 s[2:3], v6, v48
	v_or_b32_e32 v6, 18, v135
	v_writelane_b32 v255, s1, 23
	s_and_b64 s[0:1], vcc, s[2:3]
	v_cmp_ge_u32_e32 vcc, v6, v15
	v_cmp_lt_u32_e64 s[2:3], v6, v48
	v_or_b32_e32 v6, 19, v135
	s_and_b64 s[90:91], vcc, s[2:3]
	v_cmp_ge_u32_e32 vcc, v6, v15
	v_cmp_lt_u32_e64 s[2:3], v6, v48
	v_or_b32_e32 v6, 20, v135
	s_and_b64 s[92:93], vcc, s[2:3]
	v_cmp_ge_u32_e32 vcc, v6, v15
	v_cmp_lt_u32_e64 s[2:3], v6, v48
	v_or_b32_e32 v6, 21, v135
	s_and_b64 s[94:95], vcc, s[2:3]
	v_cmp_ge_u32_e32 vcc, v6, v15
	v_cmp_lt_u32_e64 s[2:3], v6, v48
	v_or_b32_e32 v6, 22, v135
	s_and_b64 s[26:27], vcc, s[2:3]
	v_cmp_ge_u32_e32 vcc, v6, v15
	v_cmp_lt_u32_e64 s[2:3], v6, v48
	v_or_b32_e32 v6, 23, v135
	s_and_b64 s[24:25], vcc, s[2:3]
	v_cmp_ge_u32_e32 vcc, v6, v15
	v_cmp_lt_u32_e64 s[2:3], v6, v48
	v_or_b32_e32 v6, 32, v135
	s_and_b64 s[72:73], vcc, s[2:3]
	v_cmp_ge_u32_e32 vcc, v6, v15
	v_cmp_lt_u32_e64 s[2:3], v6, v48
	v_or_b32_e32 v6, 33, v135
	s_and_b64 s[74:75], vcc, s[2:3]
	v_cmp_ge_u32_e32 vcc, v6, v15
	v_cmp_lt_u32_e64 s[2:3], v6, v48
	v_or_b32_e32 v6, 34, v135
	s_and_b64 s[76:77], vcc, s[2:3]
	v_cmp_ge_u32_e32 vcc, v6, v15
	v_cmp_lt_u32_e64 s[2:3], v6, v48
	v_or_b32_e32 v6, 35, v135
	s_and_b64 s[78:79], vcc, s[2:3]
	v_cmp_ge_u32_e32 vcc, v6, v15
	v_cmp_lt_u32_e64 s[2:3], v6, v48
	v_or_b32_e32 v6, 36, v135
	s_and_b64 s[80:81], vcc, s[2:3]
	v_cmp_ge_u32_e32 vcc, v6, v15
	v_cmp_lt_u32_e64 s[2:3], v6, v48
	v_or_b32_e32 v6, 37, v135
	s_and_b64 s[82:83], vcc, s[2:3]
	v_cmp_ge_u32_e32 vcc, v6, v15
	v_cmp_lt_u32_e64 s[2:3], v6, v48
	v_or_b32_e32 v6, 38, v135
	s_and_b64 s[84:85], vcc, s[2:3]
	v_cmp_ge_u32_e32 vcc, v6, v15
	v_cmp_lt_u32_e64 s[2:3], v6, v48
	v_or_b32_e32 v6, 39, v135
	s_and_b64 s[86:87], vcc, s[2:3]
	v_cmp_ge_u32_e32 vcc, v6, v15
	v_cmp_lt_u32_e64 s[2:3], v6, v48
	v_or_b32_e32 v6, 48, v135
	v_cmp_lt_u32_e64 s[54:55], v6, v48
	v_or_b32_e32 v6, 49, v135
	v_cmp_lt_u32_e64 s[56:57], v6, v48
	v_lshlrev_b32_e32 v6, 2, v19
	v_mov_b32_e32 v37, v32
	v_mov_b32_e32 v38, v32
	v_mov_b32_e32 v39, v32
	v_mov_b32_e32 v40, v32
	v_mov_b32_e32 v41, v32
	v_mov_b32_e32 v42, v32
	v_mov_b32_e32 v43, v32
	v_mov_b32_e32 v44, v32
	v_mov_b32_e32 v45, v32
	v_mov_b32_e32 v46, v32
	v_mov_b32_e32 v47, v32
	s_and_b64 s[2:3], vcc, s[2:3]
	v_sub_u32_e32 v132, s28, v6
	v_add_u32_e32 v139, v1, v2
	v_add_u32_e32 v140, v3, v0
	v_add_u32_e32 v141, v4, v192
	v_add_u32_e32 v142, v5, v192
	v_mov_b32_e32 v0, 0
	v_mov_b32_e32 v1, v138
	v_mov_b32_e32 v2, v138
	v_mov_b32_e32 v3, v138
	v_mov_b32_e32 v4, v138
	v_mov_b32_e32 v5, v138
	v_mov_b32_e32 v6, v138
	v_mov_b32_e32 v7, v138
	v_mov_b32_e32 v8, v138
	v_mov_b32_e32 v9, v138
	v_mov_b32_e32 v10, v138
	v_mov_b32_e32 v11, v138
	v_mov_b32_e32 v12, v138
	v_mov_b32_e32 v13, v138
	v_mov_b32_e32 v14, v138
	v_mov_b32_e32 v15, v138
	v_mov_b32_e32 v16, 0
	v_mov_b32_e32 v17, v138
	v_mov_b32_e32 v18, v138
	v_mov_b32_e32 v19, v138
	v_mov_b32_e32 v20, v138
	v_mov_b32_e32 v21, v138
	v_mov_b32_e32 v22, v138
	v_mov_b32_e32 v23, v138
	v_mov_b32_e32 v24, v138
	v_mov_b32_e32 v25, v138
	v_mov_b32_e32 v26, v138
	v_mov_b32_e32 v27, v138
	v_mov_b32_e32 v28, v138
	v_mov_b32_e32 v29, v138
	v_mov_b32_e32 v30, v138
	v_mov_b32_e32 v31, v138
	v_cmp_lt_u32_e64 s[58:59], v49, v48
	v_cmp_lt_u32_e64 s[60:61], v50, v48
	v_cmp_lt_u32_e64 s[62:63], v51, v48
	v_cmp_lt_u32_e64 s[64:65], v52, v48
	v_cmp_lt_u32_e64 s[66:67], v53, v48
	v_cmp_lt_u32_e64 s[68:69], v54, v48
	s_mov_b32 s100, 0xd000
	s_mov_b32 s101, 0
	s_mov_b32 s98, 0x82000
	s_mov_b32 s99, 0
	s_branch .LBB0_339

; DI void frag64_load(Frag64& f, const bf16_t* P, const bf16_t* vt, int b, int u, int kcol, int lane) {
; #pragma unroll
;   for (int i = 0; i < 4; ++i) {
;     f.k[i] = *(const u32x4*)(P + (size_t)rowOfU(b, u + (lane >> 3) + 8 * i) * NP + kcol + (lane & 7) * 8);
;     f.v[i] = *(const u32x4*)(vt + (size_t)((lane >> 2) + 16 * i) * UA + u + (lane & 3) * 8);
;   }
; }
; template <int MODE>
; DI void attn64_wave(const Params& p, int layer, int b, int hq, int qrow0, int t0, const float* rpb_lds, unsigned char* wlds) {
;     ...
;   auto tile_u = [&](int t) -> int {
;     if (t < 8) return 32 * t;
;     if (MODE == 0) return CTX + (rs + ((t - 8) >> 1)) * 64 + ((t - 8) & 1) * 32;
;     const int kt0 = t0 - 128 + 32 * (t - 8);
;     return CTX + min(max(kt0, 0), SEQ - 32);
;   };
;   auto load_tile = [&](Frag64& f, int t) { frag64_load(f, p.P, vt, b, tile_u(t), kcol, lane); };
;   unsigned char* Kw = wlds; unsigned char* Vw = wlds + W64_KB;
;   auto compute_tile = [&](const Frag64& f, int t) {
; #pragma unroll
;     for (int i = 0; i < 4; ++i) {
;       *(u32x4*)(Kw + ((lane >> 3) + 8 * i) * LDS_STRIDE + (lane & 7) * 16) = f.k[i];
;       *(u32x4*)(Vw + ((lane >> 2) + 16 * i) * W64_VSTR + (lane & 3) * 16) = f.v[i];
;     }
;     bf16x8 kf[4], vf[2][2];
; #pragma unroll
;     for (int ks = 0; ks < 4; ++ks) kf[ks] = __builtin_bit_cast(bf16x8, *(const u32x4*)(Kw + pr * LDS_STRIDE + (16 * ks + 8 * hh) * 2));
; #pragma unroll
;     for (int dh = 0; dh < 2; ++dh)
; #pragma unroll
;       for (int s2 = 0; s2 < 2; ++s2) vf[dh][s2] = __builtin_bit_cast(bf16x8, *(const u32x4*)(Vw + (32 * dh + qi) * W64_VSTR + (16 * s2 + 8 * hh) * 2));
;     f32x16 s;
; #pragma unroll
;     for (int i = 0; i < 16; ++i) s[i] = negM2;
; #pragma unroll
;     for (int ks = 0; ks < 4; ++ks) s = MFMA32(kf[ks], qf[ks], s);
;     float pe[16];
;     if (t < 8) {
; #pragma unroll
;       for (int i = 0; i < 16; ++i) pe[i] = fexp2(s[i]);
;     } else if (MODE == 0) {
;       const int kr = rs + ((t - 8) >> 1), hf = (t - 8) & 1;
;       const float* rrow = rpb + (kr - r + 7) * 31 + 15 - c;
; #pragma unroll
;       for (int i = 0; i < 16; ++i) {
;         const int kc = hf * 32 + 16 * (i >> 3) + 8 * hh + (i & 7);
;         const bool valid = (kc >= ws) && (kc < ws + 16);
;         const int kcc = min(max(kc, ws), ws + 15);
;         pe[i] = fexp2(valid ? s[i] + rrow[kcc] : -1e30f);
;       }
.LBB0_341:
	v_add_u32_e32 v126, v192, v134
	s_movk_i32 s30, 0x100
	v_mov_b32_e32 v127, s22
	v_mov_b32_e32 v143, s42
	v_cmp_gt_i32_e32 vcc, s30, v126
	v_lshl_add_u64 v[124:125], v[192:193], 1, v[130:131]
	global_load_dwordx4 v[116:119], v[124:125], off
	v_cndmask_b32_e32 v48, v127, v143, vcc
	v_add_u32_e32 v48, v48, v126
	v_mad_i64_i32 v[166:167], s[30:31], v48, s20, v[128:129]
	s_movk_i32 s30, 0xf8
	s_nop 0
	global_load_dwordx4 v[112:115], v[166:167], off
	s_nop 0
	v_lshl_add_u64 v[166:167], v[166:167], 0, s[100:101]
	global_load_dwordx4 v[120:123], v[166:167], off
	s_waitcnt vmcnt(9)
	ds_write_b128 v139, v[84:87] offset:8192
	ds_write_b128 v140, v[80:83] offset:12800
	s_waitcnt vmcnt(8)
	ds_write_b128 v139, v[88:91] offset:9344
	s_waitcnt vmcnt(7)
	ds_write_b128 v140, v[92:95] offset:14080
	s_waitcnt vmcnt(6)
	ds_write_b128 v139, v[96:99] offset:10496
	s_waitcnt vmcnt(5)
	ds_write_b128 v140, v[100:103] offset:15360
	s_waitcnt vmcnt(4)
	ds_write_b128 v139, v[104:107] offset:11648
	s_waitcnt vmcnt(3)
	ds_write_b128 v140, v[108:111] offset:16640
	ds_read_b128 v[80:83], v141 offset:8192
	ds_read_b128 v[84:87], v141 offset:8224
	s_movk_i32 s30, 0xf0
	s_nop 0
	v_lshl_add_u64 v[186:187], v[124:125], 0, s[98:99]
	global_load_dwordx4 v[92:95], v[186:187], off
	ds_read_b128 v[146:149], v141 offset:8288
	v_lshl_add_u64 v[166:167], v[166:167], 0, s[100:101]
	global_load_dwordx4 v[96:99], v[166:167], off
	s_waitcnt lgkmcnt(2)
	v_mfma_f32_32x32x16_bf16 v[48:63], v[80:83], v[72:75], v[32:47]
	s_movk_i32 s30, 0xe8
	s_nop 0
	v_lshl_add_u64 v[186:187], v[186:187], 0, s[98:99]
	global_load_dwordx4 v[100:103], v[186:187], off
	s_waitcnt lgkmcnt(1)
	v_mfma_f32_32x32x16_bf16 v[48:63], v[84:87], v[64:67], v[48:63]
	v_lshl_add_u64 v[166:167], v[166:167], 0, s[100:101]
	global_load_dwordx4 v[104:107], v[166:167], off
	ds_read_b128 v[80:83], v141 offset:8256
	s_nop 0
	v_lshl_add_u64 v[186:187], v[186:187], 0, s[98:99]
	global_load_dwordx4 v[108:111], v[186:187], off
	s_waitcnt lgkmcnt(0)
	v_mfma_f32_32x32x16_bf16 v[48:63], v[80:83], v[68:71], v[48:63]
	ds_read_b128 v[88:91], v142 offset:12800
	ds_read_b128 v[80:83], v142 offset:12832
	ds_read_b128 v[124:127], v142 offset:15360
	ds_read_b128 v[84:87], v142 offset:15392
	s_and_b64 vcc, exec, s[28:29]
	v_mfma_f32_32x32x16_bf16 v[48:63], v[146:149], v[76:79], v[48:63]
	s_cbranch_vccz .LBB0_375
	s_add_i32 s30, s43, -8
	s_lshr_b32 s30, s30, 1
	v_add_u32_e32 v143, s30, v137
	s_movk_i32 s30, 0x7c
	v_mad_u64_u32 v[146:147], s[30:31], v143, s30, v[132:133]
	v_lshl_add_u32 v147, v135, 2, v146
	ds_read_b32 v168, v147 offset:928
	ds_read_b32 v169, v147 offset:932
	ds_read_b32 v170, v147 offset:936
	ds_read_b32 v171, v147 offset:940
	ds_read_b32 v172, v147 offset:944
	ds_read_b32 v173, v147 offset:948
	ds_read_b32 v174, v147 offset:952
	ds_read_b32 v175, v147 offset:956
	ds_read_b32 v176, v147 offset:992
	ds_read_b32 v177, v147 offset:996
	ds_read_b32 v178, v147 offset:1000
	ds_read_b32 v180, v147 offset:1004
	ds_read_b32 v182, v147 offset:1008
	ds_read_b32 v183, v147 offset:1012
	ds_read_b32 v184, v147 offset:1016
	ds_read_b32 v185, v147 offset:1020
	s_waitcnt lgkmcnt(0)
	v_readlane_b32 s44, v255, 12
	v_readlane_b32 s45, v255, 13
	v_add_f32_e32 v168, v48, v168
	s_nop 0
	v_cndmask_b32_e64 v146, v237, v168, s[44:45]
	v_readlane_b32 s44, v255, 14
	v_readlane_b32 s45, v255, 15
	v_add_f32_e32 v169, v49, v169
	s_nop 0
	v_cndmask_b32_e64 v143, v237, v169, s[44:45]
	v_readlane_b32 s44, v255, 16
	v_readlane_b32 s45, v255, 17
	v_add_f32_e32 v170, v50, v170
	s_nop 0
	v_cndmask_b32_e64 v148, v237, v170, s[44:45]
	v_readlane_b32 s44, v255, 18
	v_readlane_b32 s45, v255, 19
	v_add_f32_e32 v171, v51, v171
	s_nop 0
	v_cndmask_b32_e64 v149, v237, v171, s[44:45]
	v_readlane_b32 s44, v255, 20
	v_readlane_b32 s45, v255, 21
	v_add_f32_e32 v172, v52, v172
	s_nop 0
	v_cndmask_b32_e64 v159, v237, v172, s[44:45]
	v_readlane_b32 s44, v255, 22
	v_readlane_b32 s45, v255, 23
	v_add_f32_e32 v173, v53, v173
	s_nop 0
	v_cndmask_b32_e64 v160, v237, v173, s[44:45]
	v_add_f32_e32 v174, v54, v174
	s_nop 0
	v_cndmask_b32_e64 v161, v237, v174, s[50:51]
	v_add_f32_e32 v175, v55, v175
	s_nop 0
	v_cndmask_b32_e64 v162, v237, v175, s[52:53]
	v_add_f32_e32 v176, v56, v176
	s_nop 0
	v_cndmask_b32_e64 v163, v237, v176, s[46:47]
	v_add_f32_e32 v177, v57, v177
	s_nop 0
	v_cndmask_b32_e64 v151, v237, v177, s[0:1]
	v_add_f32_e32 v178, v58, v178
	s_nop 0
	v_cndmask_b32_e64 v150, v237, v178, s[90:91]
	v_add_f32_e32 v180, v59, v180
	s_nop 0
	v_cndmask_b32_e64 v157, v237, v180, s[92:93]
	v_add_f32_e32 v182, v60, v182
	s_nop 0
	v_cndmask_b32_e64 v156, v237, v182, s[94:95]
	v_add_f32_e32 v183, v61, v183
	s_nop 0
	v_cndmask_b32_e64 v158, v237, v183, s[26:27]
	v_add_f32_e32 v184, v62, v184
	s_nop 0
	v_cndmask_b32_e64 v165, v237, v184, s[24:25]
	v_add_f32_e32 v185, v63, v185
	s_nop 0
	v_cndmask_b32_e64 v164, v237, v185, s[72:73]
	v_exp_f32_e32 v158, v158
	v_exp_f32_e32 v156, v156
	v_exp_f32_e32 v157, v157
	v_exp_f32_e32 v150, v150
	v_exp_f32_e32 v151, v151
	v_exp_f32_e32 v147, v163
	v_exp_f32_e32 v163, v162
	v_exp_f32_e32 v161, v161
	v_exp_f32_e32 v162, v160
	v_exp_f32_e32 v159, v159
	v_exp_f32_e32 v160, v149
	v_exp_f32_e32 v148, v148
	v_exp_f32_e32 v149, v143
	v_exp_f32_e32 v143, v146
	v_exp_f32_e32 v146, v165
	s_branch .LBB0_377

; DI void frag64_load(Frag64& f, const bf16_t* P, const bf16_t* vt, int b, int u, int kcol, int lane) {
; #pragma unroll
;   for (int i = 0; i < 4; ++i) {
;     f.k[i] = *(const u32x4*)(P + (size_t)rowOfU(b, u + (lane >> 3) + 8 * i) * NP + kcol + (lane & 7) * 8);
;     f.v[i] = *(const u32x4*)(vt + (size_t)((lane >> 2) + 16 * i) * UA + u + (lane & 3) * 8);
;   }
; }
; template <int MODE>
; DI void attn64_wave(const Params& p, int layer, int b, int hq, int qrow0, int t0, const float* rpb_lds, unsigned char* wlds) {
;     ...
;   auto tile_u = [&](int t) -> int {
;     if (t < 8) return 32 * t;
;     if (MODE == 0) return CTX + (rs + ((t - 8) >> 1)) * 64 + ((t - 8) & 1) * 32;
;     const int kt0 = t0 - 128 + 32 * (t - 8);
;     return CTX + min(max(kt0, 0), SEQ - 32);
;   };
;   auto load_tile = [&](Frag64& f, int t) { frag64_load(f, p.P, vt, b, tile_u(t), kcol, lane); };
;   unsigned char* Kw = wlds; unsigned char* Vw = wlds + W64_KB;
;   auto compute_tile = [&](const Frag64& f, int t) {
; #pragma unroll
;     for (int i = 0; i < 4; ++i) {
;       *(u32x4*)(Kw + ((lane >> 3) + 8 * i) * LDS_STRIDE + (lane & 7) * 16) = f.k[i];
;       *(u32x4*)(Vw + ((lane >> 2) + 16 * i) * W64_VSTR + (lane & 3) * 16) = f.v[i];
;     }
;     bf16x8 kf[4], vf[2][2];
; #pragma unroll
;     for (int ks = 0; ks < 4; ++ks) kf[ks] = __builtin_bit_cast(bf16x8, *(const u32x4*)(Kw + pr * LDS_STRIDE + (16 * ks + 8 * hh) * 2));
; #pragma unroll
;     for (int dh = 0; dh < 2; ++dh)
; #pragma unroll
;       for (int s2 = 0; s2 < 2; ++s2) vf[dh][s2] = __builtin_bit_cast(bf16x8, *(const u32x4*)(Vw + (32 * dh + qi) * W64_VSTR + (16 * s2 + 8 * hh) * 2));
;     f32x16 s;
; #pragma unroll
;     for (int i = 0; i < 16; ++i) s[i] = negM2;
; #pragma unroll
;     for (int ks = 0; ks < 4; ++ks) s = MFMA32(kf[ks], qf[ks], s);
;     float pe[16];
;     if (t < 8) {
; #pragma unroll
;       for (int i = 0; i < 16; ++i) pe[i] = fexp2(s[i]);
;     } else if (MODE == 0) {
;       const int kr = rs + ((t - 8) >> 1), hf = (t - 8) & 1;
;       const float* rrow = rpb + (kr - r + 7) * 31 + 15 - c;
; #pragma unroll
;       for (int i = 0; i < 16; ++i) {
;         const int kc = hf * 32 + 16 * (i >> 3) + 8 * hh + (i & 7);
;         const bool valid = (kc >= ws) && (kc < ws + 16);
;         const int kcc = min(max(kc, ws), ws + 15);
;         pe[i] = fexp2(valid ? s[i] + rrow[kcc] : -1e30f);
;       }
.LBB0_381:
	v_add_u32_e32 v126, v48, v134
	s_movk_i32 s45, 0x100
	v_mov_b32_e32 v127, s22
	v_mov_b32_e32 v143, s42
	v_cmp_gt_i32_e32 vcc, s45, v126
	s_movk_i32 s45, 0xf8
	v_ashrrev_i32_e32 v49, 31, v48
	v_cndmask_b32_e32 v50, v127, v143, vcc
	v_add_u32_e32 v50, v50, v126
	v_mad_i64_i32 v[166:167], vcc, v50, s20, v[128:129]
	v_lshl_add_u64 v[124:125], v[48:49], 1, v[130:131]
	global_load_dwordx4 v[84:87], v[166:167], off
	v_lshl_add_u64 v[166:167], v[166:167], 0, s[100:101]
	global_load_dwordx4 v[80:83], v[124:125], off
	global_load_dwordx4 v[88:91], v[166:167], off
	s_waitcnt vmcnt(9)
	ds_write_b128 v139, v[112:115] offset:8192
	ds_write_b128 v140, v[116:119] offset:12800
	s_waitcnt vmcnt(8)
	ds_write_b128 v139, v[120:123] offset:9344
	s_waitcnt vmcnt(7)
	ds_write_b128 v140, v[92:95] offset:14080
	s_waitcnt vmcnt(6)
	ds_write_b128 v139, v[96:99] offset:10496
	s_waitcnt vmcnt(5)
	ds_write_b128 v140, v[100:103] offset:15360
	s_waitcnt vmcnt(4)
	ds_write_b128 v139, v[104:107] offset:11648
	s_waitcnt vmcnt(3)
	ds_write_b128 v140, v[108:111] offset:16640
	ds_read_b128 v[100:103], v141 offset:8192
	ds_read_b128 v[104:107], v141 offset:8224
	s_movk_i32 s45, 0xf0
	s_nop 0
	v_lshl_add_u64 v[186:187], v[124:125], 0, s[98:99]
	global_load_dwordx4 v[92:95], v[186:187], off
	s_movk_i32 s45, 0xe8
	v_lshl_add_u64 v[166:167], v[166:167], 0, s[100:101]
	global_load_dwordx4 v[96:99], v[166:167], off
	s_waitcnt lgkmcnt(1)
	v_mfma_f32_32x32x16_bf16 v[48:63], v[100:103], v[72:75], v[32:47]
	ds_read_b128 v[146:149], v141 offset:8288
	s_nop 0
	v_lshl_add_u64 v[186:187], v[186:187], 0, s[98:99]
	global_load_dwordx4 v[100:103], v[186:187], off
	s_waitcnt lgkmcnt(1)
	v_mfma_f32_32x32x16_bf16 v[48:63], v[104:107], v[64:67], v[48:63]
	ds_read_b128 v[108:111], v141 offset:8256
	v_lshl_add_u64 v[166:167], v[166:167], 0, s[100:101]
	global_load_dwordx4 v[104:107], v[166:167], off
	s_nop 0
	v_lshl_add_u64 v[186:187], v[186:187], 0, s[98:99]
	s_waitcnt lgkmcnt(0)
	v_mfma_f32_32x32x16_bf16 v[48:63], v[108:111], v[68:71], v[48:63]
	global_load_dwordx4 v[108:111], v[186:187], off
	ds_read_b128 v[120:123], v142 offset:12800
	ds_read_b128 v[112:115], v142 offset:12832
	ds_read_b128 v[124:127], v142 offset:15360
	ds_read_b128 v[116:119], v142 offset:15392
	s_and_b64 vcc, exec, s[28:29]
	v_mfma_f32_32x32x16_bf16 v[48:63], v[146:149], v[76:79], v[48:63]
	s_cbranch_vccz .LBB0_415
	s_add_i32 s28, s43, -7
	s_lshr_b32 s28, s28, 1
	v_add_u32_e32 v143, s28, v137
	s_movk_i32 s28, 0x7c
	v_mad_u64_u32 v[146:147], s[28:29], v143, s28, v[132:133]
	v_lshl_add_u32 v147, v135, 2, v146
	ds_read_b32 v168, v147 offset:1056
	ds_read_b32 v169, v147 offset:1060
	ds_read_b32 v170, v147 offset:1064
	ds_read_b32 v171, v147 offset:1068
	ds_read_b32 v172, v147 offset:1072
	ds_read_b32 v173, v147 offset:1076
	ds_read_b32 v174, v147 offset:1080
	ds_read_b32 v175, v147 offset:1084
	ds_read_b32 v176, v147 offset:1120
	ds_read_b32 v177, v147 offset:1124
	ds_read_b32 v178, v147 offset:1128
	ds_read_b32 v180, v147 offset:1132
	ds_read_b32 v182, v147 offset:1136
	ds_read_b32 v183, v147 offset:1140
	ds_read_b32 v184, v147 offset:1144
	ds_read_b32 v185, v147 offset:1148
	s_waitcnt lgkmcnt(0)
	v_add_f32_e32 v168, v48, v168
	s_nop 0
	v_cndmask_b32_e64 v146, v237, v168, s[74:75]
	v_add_f32_e32 v169, v49, v169
	s_nop 0
	v_cndmask_b32_e64 v143, v237, v169, s[76:77]
	v_add_f32_e32 v170, v50, v170
	s_nop 0
	v_cndmask_b32_e64 v148, v237, v170, s[78:79]
	v_add_f32_e32 v171, v51, v171
	s_nop 0
	v_cndmask_b32_e64 v149, v237, v171, s[80:81]
	v_add_f32_e32 v172, v52, v172
	s_nop 0
	v_cndmask_b32_e64 v150, v237, v172, s[82:83]
	v_add_f32_e32 v173, v53, v173
	s_nop 0
	v_cndmask_b32_e64 v151, v237, v173, s[84:85]
	v_add_f32_e32 v174, v54, v174
	s_nop 0
	v_cndmask_b32_e64 v161, v237, v174, s[86:87]
	v_add_f32_e32 v175, v55, v175
	s_nop 0
	v_cndmask_b32_e64 v162, v237, v175, s[2:3]
	v_add_f32_e32 v176, v56, v176
	s_nop 0
	v_cndmask_b32_e64 v163, v237, v176, s[54:55]
	v_add_f32_e32 v177, v57, v177
	s_nop 0
	v_cndmask_b32_e64 v157, v237, v177, s[56:57]
	v_add_f32_e32 v178, v58, v178
	s_nop 0
	v_cndmask_b32_e64 v156, v237, v178, s[58:59]
	v_add_f32_e32 v180, v59, v180
	s_nop 0
	v_cndmask_b32_e64 v159, v237, v180, s[60:61]
	v_add_f32_e32 v182, v60, v182
	s_nop 0
	v_cndmask_b32_e64 v158, v237, v182, s[62:63]
	v_add_f32_e32 v183, v61, v183
	s_nop 0
	v_cndmask_b32_e64 v160, v237, v183, s[64:65]
	v_add_f32_e32 v184, v62, v184
	s_nop 0
	v_cndmask_b32_e64 v165, v237, v184, s[66:67]
	v_add_f32_e32 v185, v63, v185
	s_nop 0
	v_cndmask_b32_e64 v164, v237, v185, s[68:69]
	v_exp_f32_e32 v160, v160
	v_exp_f32_e32 v158, v158
	v_exp_f32_e32 v159, v159
	v_exp_f32_e32 v156, v156
	v_exp_f32_e32 v157, v157
	v_exp_f32_e32 v147, v163
	v_exp_f32_e32 v163, v162
	v_exp_f32_e32 v161, v161
	v_exp_f32_e32 v162, v151
	v_exp_f32_e32 v150, v150
	v_exp_f32_e32 v151, v149
	v_exp_f32_e32 v148, v148
	v_exp_f32_e32 v149, v143
	v_exp_f32_e32 v143, v146
	v_exp_f32_e32 v146, v165
	s_branch .LBB0_338

; DI int ltid() { int t = threadIdx.x & 255; asm volatile("" : "+v"(t)); return t; }
; template <int MODE>
; DI void attn64_wave(const Params& p, int layer, int b, int hq, int qrow0, int t0, const float* rpb_lds, unsigned char* wlds) {
;   constexpr bool isC = (MODE == 0 || MODE == 2);
;   const int lane = ltid() & 63, qi = lane & 31, hh = lane >> 5;
;   const int pr = (qi & 19) | ((qi & 4) << 1) | ((qi & 8) >> 1);
;   const float* gqp = (isC ? p.na_q_gain : p.sw_q_gain) + layer * 64;
;   const float* gkp = (isC ? p.na_k_gain : p.sw_k_gain) + layer * 64;
;   const float gq = wave_max(fabsf(gqp[lane])), gk = wave_max(fabsf(gkp[lane]));
;   const float negM2 = -(0.125f * LOG2E * 64.f * 1.02f) * gq * gk;
;   const int kvh = isC ? hq : (hq >> 1);
;   const int qcol = isC ? 2048 + 64 * hq : 2816 + 64 * hq;
;   const int kcol = isC ? 2304 + 64 * hq : 3072 + 64 * kvh;
;   const bf16_t* vt = isC ? p.VtC + (size_t)(b * 4 + hq) * 64 * UA : p.VtD + (size_t)(b * 2 + kvh) * 64 * UA;
;   const bf16_t* qp = p.P + (size_t)(qrow0 + qi) * NP + qcol + 8 * hh;
;   bf16x8 qf[4];
; #pragma unroll
;   for (int ks = 0; ks < 4; ++ks) qf[ks] = *(const bf16x8*)(qp + ks * 16);
;   f32x16 o[2];
; #pragma unroll
;   for (int dh = 0; dh < 2; ++dh)
; #pragma unroll
;     for (int i = 0; i < 16; ++i) o[dh][i] = 0.f;
;   float ls = 0.f;
;   constexpr int NT = MODE == 0 ? 24 : (MODE == 1 ? 18 : 8);
;   const int r = t0 >> 6, c = (t0 & 63) + qi;
;   const int rs = min(max(r - 4, 0), 248), ws = min(max(c - 8, 0), 48);
;   const float* rpb = rpb_lds + hq * 465;
;   const int qt = t0 + qi;
.LBB0_419:
	s_nop 2
	v_mov_b32_e32 v10, v212
	v_readlane_b32 s2, v255, 4
	v_and_b32_e32 v4, 63, v10
	v_lshlrev_b32_e32 v0, 2, v4
	v_readlane_b32 s3, v255, 5
	v_readlane_b32 s24, v255, 6
	v_readlane_b32 s25, v255, 7
	v_cmp_lt_i32_e32 vcc, v218, v217
	v_lshlrev_b32_e32 v23, 4, v4
	v_mov_b32_e32 v5, v193
	global_load_dword v11, v0, s[2:3]
	v_cndmask_b32_e32 v2, v216, v218, vcc
	global_load_dword v12, v0, s[24:25]
	s_and_b32 s2, s38, 0x3f80
	s_sub_i32 s3, s40, s27
	v_add_u32_e32 v132, s2, v152
	s_lshr_b32 s2, s3, 7
	s_ashr_i32 s27, s3, 9
	v_cmp_lt_i32_e32 vcc, v219, v217
	s_bfe_u32 s26, s3, 0x20007
	s_lshl_b32 s3, s3, 7
	s_bfe_u32 s29, s2, 0x10001
	s_lshl_b32 s2, s27, 1
	v_cndmask_b32_e32 v6, v216, v219, vcc
	v_cmp_lt_i32_e32 vcc, v220, v217
	s_and_b32 s3, s3, 0x3f80
	s_lshl_b32 s22, s26, 6
	s_or_b32 s2, s29, s2
	v_cndmask_b32_e32 v8, v216, v220, vcc
	s_lshl_b32 s28, s27, 14
	v_add_u32_e32 v20, s3, v152
	s_mov_b64 s[44:45], s[22:23]
	s_lshl_b32 s22, s26, 7
	s_mul_hi_i32 s3, s2, 0x208000
	s_mul_i32 s2, s2, 0x208000
	v_cmp_lt_i32_e32 vcc, v221, v217
	v_lshlrev_b32_e32 v133, 2, v2
	v_lshlrev_b32_e32 v16, 2, v8
	v_lshlrev_b32_e32 v2, 1, v10
	v_lshlrev_b32_e32 v8, 4, v10
	s_add_u32 s2, s86, s2
	v_cndmask_b32_e32 v9, v216, v221, vcc
	v_and_b32_e32 v18, 31, v10
	v_and_b32_e32 v21, 8, v2
	v_and_b32_e32 v2, 0x70, v8
	v_add_u32_e32 v8, s28, v20
	v_and_b32_e32 v4, 48, v23
	s_addc_u32 s3, s87, s3
	v_mov_b64_e32 v[0:1], s[78:79]
	v_lshlrev_b32_e32 v17, 2, v9
	v_or_b32_e32 v144, v18, v8
	v_lshl_add_u64 v[8:9], s[2:3], 0, v[4:5]
	v_bfe_u32 v155, v10, 5, 1
	v_mad_i64_i32 v[0:1], s[24:25], v144, s20, v[0:1]
	v_cmp_lt_i32_e32 vcc, v222, v217
	v_lshlrev_b32_e32 v15, 2, v6
	v_lshrrev_b32_e32 v6, 1, v10
	v_bfe_u32 v19, v10, 2, 4
	v_lshlrev_b32_e32 v192, 4, v155
	v_lshl_add_u64 v[0:1], v[0:1], 0, s[22:23]
	v_cndmask_b32_e32 v13, v216, v222, vcc
	v_cmp_lt_i32_e32 vcc, v223, v217
	v_mov_b32_e32 v7, v193
	v_and_b32_e32 v22, 4, v6
	v_mul_u32_u24_e32 v6, 0x8200, v19
	v_lshl_add_u64 v[0:1], v[0:1], 0, v[192:193]
	s_mov_b64 s[2:3], 0x1600
	v_cndmask_b32_e32 v14, v216, v223, vcc
	v_lshl_add_u64 v[128:129], v[8:9], 0, v[6:7]
	v_lshl_add_u64 v[6:7], v[0:1], 0, s[2:3]
	v_add_co_u32_e32 v0, vcc, s63, v0
	global_load_dwordx4 v[80:83], v[128:129], off
	s_nop 0
	v_addc_co_u32_e32 v1, vcc, 0, v1, vcc
	global_load_dwordx4 v[64:67], v[6:7], off offset:32
	global_load_dwordx4 v[68:71], v[6:7], off offset:64
	global_load_dwordx4 v[72:75], v[0:1], off offset:1536
	global_load_dwordx4 v[76:79], v[6:7], off offset:96
	s_lshl_b32 s24, s29, 7
	s_add_u32 s24, s78, s24
	v_mov_b32_e32 v3, v193
	s_addc_u32 s25, s79, 0
	v_lshl_add_u64 v[2:3], s[24:25], 0, v[2:3]
	s_mov_b64 s[2:3], 0x1800
	v_lshl_add_u64 v[130:131], v[2:3], 0, s[2:3]
	v_lshlrev_b32_e32 v13, 2, v13
	s_lshl_b32 s22, s27, 8
	v_bfe_u32 v134, v10, 3, 3
	s_add_i32 s22, s22, 0x8000
	v_lshlrev_b32_e32 v14, 2, v14
	v_mov_b32_e32 v135, 0
	s_waitcnt vmcnt(6)
	v_and_b32_e32 v5, 0x7fffffff, v11
	ds_bpermute_b32 v5, v133, v5
	v_max_f32_e64 v0, |v11|, |v11|
	s_waitcnt vmcnt(5)
	v_and_b32_e32 v2, 0x7fffffff, v12
	ds_bpermute_b32 v2, v133, v2
	v_max_f32_e64 v3, |v12|, |v12|
	s_waitcnt lgkmcnt(1)
	v_max_f32_e32 v1, v5, v5
	v_max_f32_e32 v0, v0, v1
	ds_bpermute_b32 v1, v15, v0
	s_waitcnt lgkmcnt(1)
	v_max_f32_e32 v2, v2, v2
	v_max_f32_e32 v2, v3, v2
	ds_bpermute_b32 v3, v15, v2
	v_or_b32_e32 v5, s22, v134
	s_waitcnt lgkmcnt(1)
	v_max_f32_e32 v1, v1, v1
	v_max_f32_e32 v0, v0, v1
	ds_bpermute_b32 v1, v16, v0
	s_waitcnt lgkmcnt(1)
	v_max_f32_e32 v3, v3, v3
	v_max_f32_e32 v2, v2, v3
	ds_bpermute_b32 v3, v16, v2
	v_or_b32_e32 v8, 8, v5
	s_waitcnt lgkmcnt(1)
; DI int ltid() { int t = threadIdx.x & 255; asm volatile("" : "+v"(t)); return t; }
; DI void frag64_load(Frag64& f, const bf16_t* P, const bf16_t* vt, int b, int u, int kcol, int lane) {
; #pragma unroll
;   for (int i = 0; i < 4; ++i) {
;     f.k[i] = *(const u32x4*)(P + (size_t)rowOfU(b, u + (lane >> 3) + 8 * i) * NP + kcol + (lane & 7) * 8);
;     f.v[i] = *(const u32x4*)(vt + (size_t)((lane >> 2) + 16 * i) * UA + u + (lane & 3) * 8);
;   }
; }
; template <int MODE>
; DI void attn64_wave(const Params& p, int layer, int b, int hq, int qrow0, int t0, const float* rpb_lds, unsigned char* wlds) {
;     ...
;   const int lane = ltid() & 63, qi = lane & 31, hh = lane >> 5;
;   const int pr = (qi & 19) | ((qi & 4) << 1) | ((qi & 8) >> 1);
;   const float* gqp = (isC ? p.na_q_gain : p.sw_q_gain) + layer * 64;
;   const float* gkp = (isC ? p.na_k_gain : p.sw_k_gain) + layer * 64;
;   const float gq = wave_max(fabsf(gqp[lane])), gk = wave_max(fabsf(gkp[lane]));
;   const float negM2 = -(0.125f * LOG2E * 64.f * 1.02f) * gq * gk;
;   const int kvh = isC ? hq : (hq >> 1);
;   const int qcol = isC ? 2048 + 64 * hq : 2816 + 64 * hq;
;   const int kcol = isC ? 2304 + 64 * hq : 3072 + 64 * kvh;
;   const bf16_t* vt = isC ? p.VtC + (size_t)(b * 4 + hq) * 64 * UA : p.VtD + (size_t)(b * 2 + kvh) * 64 * UA;
;   const bf16_t* qp = p.P + (size_t)(qrow0 + qi) * NP + qcol + 8 * hh;
;   bf16x8 qf[4];
; #pragma unroll
;   for (int ks = 0; ks < 4; ++ks) qf[ks] = *(const bf16x8*)(qp + ks * 16);
;   f32x16 o[2];
; #pragma unroll
;   for (int dh = 0; dh < 2; ++dh)
; #pragma unroll
;     for (int i = 0; i < 16; ++i) o[dh][i] = 0.f;
;   float ls = 0.f;
;   constexpr int NT = MODE == 0 ? 24 : (MODE == 1 ? 18 : 8);
;   const int r = t0 >> 6, c = (t0 & 63) + qi;
;   const int rs = min(max(r - 4, 0), 248), ws = min(max(c - 8, 0), 48);
;   const float* rpb = rpb_lds + hq * 465;
;   const int qt = t0 + qi;
	v_max_f32_e32 v1, v1, v1
	v_max_f32_e32 v6, v0, v1
	ds_bpermute_b32 v7, v17, v6
	s_waitcnt lgkmcnt(1)
	v_max_f32_e32 v3, v3, v3
	v_mad_u64_u32 v[0:1], s[2:3], v5, s20, v[130:131]
	v_max_f32_e32 v9, v2, v3
	s_waitcnt lgkmcnt(0)
	v_max_f32_e32 v7, v7, v7
	v_max_f32_e32 v6, v6, v7
	ds_bpermute_b32 v7, v13, v6
	ds_bpermute_b32 v11, v17, v9
	s_mov_b32 s29, 0
	s_mov_b32 s27, 32
	v_ashrrev_i32_e32 v145, 31, v144
	s_waitcnt lgkmcnt(1)
	v_max_f32_e32 v2, v7, v7
	v_max_f32_e32 v6, v6, v2
	v_mad_u64_u32 v[2:3], s[2:3], v8, s20, v[130:131]
	global_load_dwordx4 v[84:87], v[0:1], off
	global_load_dwordx4 v[88:91], v[2:3], off
	v_add_co_u32_e32 v0, vcc, s61, v128
	v_lshlrev_b32_e32 v3, 3, v155
	s_nop 0
	v_addc_co_u32_e32 v1, vcc, 0, v129, vcc
	global_load_dwordx4 v[92:95], v[0:1], off
	v_or_b32_e32 v0, 16, v5
	v_mad_u64_u32 v[0:1], s[2:3], v0, s20, v[130:131]
	global_load_dwordx4 v[96:99], v[0:1], off
	v_add_co_u32_e32 v0, vcc, s62, v128
	s_addk_i32 s28, 0xff00
	s_nop 0
	v_addc_co_u32_e32 v1, vcc, 0, v129, vcc
	global_load_dwordx4 v[100:103], v[0:1], off
	v_or_b32_e32 v0, 24, v5
	v_mad_u64_u32 v[0:1], s[2:3], v0, s20, v[130:131]
	global_load_dwordx4 v[104:107], v[0:1], off
	v_add_co_u32_e32 v0, vcc, 0x186000, v128
	v_and_b32_e32 v5, 19, v10
	s_nop 0
	v_addc_co_u32_e32 v1, vcc, 0, v129, vcc
	global_load_dwordx4 v[108:111], v[0:1], off
	s_waitcnt lgkmcnt(0)
	v_max_f32_e32 v1, v11, v11
	v_max_f32_e32 v1, v9, v1
	ds_bpermute_b32 v2, v13, v1
	ds_bpermute_b32 v0, v14, v6
	v_add_u32_e32 v136, 0xfffffe80, v20
	v_sub_u32_e32 v137, v3, v18
	v_mov_b32_e32 v3, v135
	s_waitcnt lgkmcnt(1)
	v_max_f32_e32 v2, v2, v2
	v_max_f32_e32 v1, v1, v2
	ds_bpermute_b32 v2, v14, v1
	s_waitcnt lgkmcnt(1)
	v_max_f32_e32 v0, v0, v0
	v_max_f32_e32 v0, v6, v0
	v_mul_f32_e32 v0, 0xc13c5bb7, v0
	v_mad_u32_u24 v6, v18, s60, v153
	s_waitcnt lgkmcnt(0)
	v_max_f32_e32 v2, v2, v2
	v_max_f32_e32 v1, v1, v2
	v_or3_b32 v2, v5, v21, v22
	v_mul_f32_e32 v32, v0, v1
	v_mad_u32_u24 v0, v134, s59, v153
	v_and_b32_e32 v1, 0x70, v23
	v_mad_u32_u24 v5, v19, s60, v153
	v_mad_u32_u24 v2, v2, s59, v153
	v_mov_b32_e32 v33, v32
	v_mov_b32_e32 v34, v32
	v_mov_b32_e32 v35, v32
	v_mov_b32_e32 v36, v32
	v_mov_b32_e32 v37, v32
	v_mov_b32_e32 v38, v32
	v_mov_b32_e32 v39, v32
	v_mov_b32_e32 v40, v32
	v_mov_b32_e32 v41, v32
	v_mov_b32_e32 v42, v32
	v_mov_b32_e32 v43, v32
	v_mov_b32_e32 v44, v32
	v_mov_b32_e32 v45, v32
	v_mov_b32_e32 v46, v32
	v_mov_b32_e32 v47, v32
	v_add_u32_e32 v138, v0, v1
	v_add_u32_e32 v139, v5, v4
	v_add_u32_e32 v140, v2, v192
	v_add_u32_e32 v141, v6, v192
	v_mov_b32_e32 v0, 0
	v_mov_b32_e32 v1, v135
	v_mov_b32_e32 v2, v135
	v_mov_b32_e32 v4, v135
	v_mov_b32_e32 v5, v135
	v_mov_b32_e32 v6, v135
	v_mov_b32_e32 v7, v135
	v_mov_b32_e32 v8, v135
	v_mov_b32_e32 v9, v135
	v_mov_b32_e32 v10, v135
	v_mov_b32_e32 v11, v135
	v_mov_b32_e32 v12, v135
	v_mov_b32_e32 v13, v135
	v_mov_b32_e32 v14, v135
	v_mov_b32_e32 v15, v135
	v_mov_b32_e32 v16, 0
	v_mov_b32_e32 v17, v135
	v_mov_b32_e32 v18, v135
	v_mov_b32_e32 v19, v135
	v_mov_b32_e32 v20, v135
	v_mov_b32_e32 v21, v135
	v_mov_b32_e32 v22, v135
	v_mov_b32_e32 v23, v135
	v_mov_b32_e32 v24, v135
	v_mov_b32_e32 v25, v135
	v_mov_b32_e32 v26, v135
	v_mov_b32_e32 v27, v135
	v_mov_b32_e32 v28, v135
	v_mov_b32_e32 v29, v135
	v_mov_b32_e32 v30, v135
	v_mov_b32_e32 v31, v135
	v_readfirstlane_b32 s98, v132
	s_add_i32 s98, s98, 0xffffff80
	s_cmp_lt_u32 s98, 0x3ee1
	s_cselect_b64 s[98:99], -1, 0
	s_mov_b32 s46, 0xd000
	s_mov_b32 s47, 0
	s_mov_b32 s50, 0x82000
	s_mov_b32 s51, 0
	s_branch .LBB0_421

; DI void frag64_load(Frag64& f, const bf16_t* P, const bf16_t* vt, int b, int u, int kcol, int lane) {
; #pragma unroll
;   for (int i = 0; i < 4; ++i) {
;     f.k[i] = *(const u32x4*)(P + (size_t)rowOfU(b, u + (lane >> 3) + 8 * i) * NP + kcol + (lane & 7) * 8);
;     f.v[i] = *(const u32x4*)(vt + (size_t)((lane >> 2) + 16 * i) * UA + u + (lane & 3) * 8);
;   }
; }
; template <int MODE>
; DI void attn64_wave(const Params& p, int layer, int b, int hq, int qrow0, int t0, const float* rpb_lds, unsigned char* wlds) {
;     ...
;   auto tile_u = [&](int t) -> int {
;     if (t < 8) return 32 * t;
;     if (MODE == 0) return CTX + (rs + ((t - 8) >> 1)) * 64 + ((t - 8) & 1) * 32;
;     const int kt0 = t0 - 128 + 32 * (t - 8);
;     return CTX + min(max(kt0, 0), SEQ - 32);
;   };
;   auto load_tile = [&](Frag64& f, int t) { frag64_load(f, p.P, vt, b, tile_u(t), kcol, lane); };
;   unsigned char* Kw = wlds; unsigned char* Vw = wlds + W64_KB;
;   auto compute_tile = [&](const Frag64& f, int t) {
; #pragma unroll
;     for (int i = 0; i < 4; ++i) {
;       *(u32x4*)(Kw + ((lane >> 3) + 8 * i) * LDS_STRIDE + (lane & 7) * 16) = f.k[i];
;       *(u32x4*)(Vw + ((lane >> 2) + 16 * i) * W64_VSTR + (lane & 3) * 16) = f.v[i];
;     }
;     bf16x8 kf[4], vf[2][2];
; #pragma unroll
;     for (int ks = 0; ks < 4; ++ks) kf[ks] = __builtin_bit_cast(bf16x8, *(const u32x4*)(Kw + pr * LDS_STRIDE + (16 * ks + 8 * hh) * 2));
; #pragma unroll
;     for (int dh = 0; dh < 2; ++dh)
; #pragma unroll
;       for (int s2 = 0; s2 < 2; ++s2) vf[dh][s2] = __builtin_bit_cast(bf16x8, *(const u32x4*)(Vw + (32 * dh + qi) * W64_VSTR + (16 * s2 + 8 * hh) * 2));
;     f32x16 s;
; #pragma unroll
;     for (int i = 0; i < 16; ++i) s[i] = negM2;
; #pragma unroll
;     for (int ks = 0; ks < 4; ++ks) s = MFMA32(kf[ks], qf[ks], s);
;     float pe[16];
;     if (t < 8) {
; #pragma unroll
;       for (int i = 0; i < 16; ++i) pe[i] = fexp2(s[i]);
;     } else if (MODE == 0) {
;       const int kr = rs + ((t - 8) >> 1), hf = (t - 8) & 1;
;       const float* rrow = rpb + (kr - r + 7) * 31 + 15 - c;
; #pragma unroll
;       for (int i = 0; i < 16; ++i) {
;         const int kc = hf * 32 + 16 * (i >> 3) + 8 * hh + (i & 7);
;         const bool valid = (kc >= ws) && (kc < ws + 16);
;         const int kcc = min(max(kc, ws), ws + 15);
;         pe[i] = fexp2(valid ? s[i] + rrow[kcc] : -1e30f);
;       }
;     } else {
.LBB0_421:
	v_add_u32_e32 v146, s27, v132
	s_cmp_gt_u32 s29, 7
	v_add_u32_e32 v142, 0xfffffe80, v146
	s_cselect_b64 s[24:25], -1, 0
	s_cmp_lt_u32 s29, 8
	v_med3_i32 v48, v142, 0, v236
	v_add_u32_e32 v48, 0x100, v48
	v_mov_b32_e32 v49, s27
	s_cselect_b64 vcc, -1, 0
	v_cndmask_b32_e32 v192, v48, v49, vcc
	v_add_u32_e32 v126, v192, v134
	s_movk_i32 s2, 0x100
	v_mov_b32_e32 v127, s28
	v_mov_b32_e32 v143, s22
	v_cmp_gt_u32_e32 vcc, s2, v126
	v_lshl_add_u64 v[124:125], v[192:193], 1, v[128:129]
	global_load_dwordx4 v[116:119], v[124:125], off
	v_cndmask_b32_e32 v48, v127, v143, vcc
	v_add_u32_e32 v48, v48, v126
	v_mad_i64_i32 v[166:167], s[2:3], v48, s20, v[130:131]
	s_movk_i32 s2, 0xf8
	s_nop 0
	global_load_dwordx4 v[112:115], v[166:167], off
	s_nop 0
	v_lshl_add_u64 v[166:167], v[166:167], 0, s[46:47]
	global_load_dwordx4 v[120:123], v[166:167], off
	s_waitcnt vmcnt(9)
	ds_write_b128 v138, v[84:87] offset:8192
	s_waitcnt vmcnt(8)
	ds_write_b128 v139, v[80:83] offset:12800
	s_waitcnt vmcnt(8)
	ds_write_b128 v138, v[88:91] offset:9344
	s_waitcnt vmcnt(7)
	ds_write_b128 v139, v[92:95] offset:14080
	s_waitcnt vmcnt(6)
	ds_write_b128 v138, v[96:99] offset:10496
	s_waitcnt vmcnt(5)
	ds_write_b128 v139, v[100:103] offset:15360
	s_waitcnt vmcnt(4)
	ds_write_b128 v138, v[104:107] offset:11648
	s_waitcnt vmcnt(3)
	ds_write_b128 v139, v[108:111] offset:16640
	ds_read_b128 v[80:83], v140 offset:8192
	ds_read_b128 v[84:87], v140 offset:8224
	s_movk_i32 s2, 0xf0
	s_nop 0
	v_lshl_add_u64 v[186:187], v[124:125], 0, s[50:51]
	global_load_dwordx4 v[92:95], v[186:187], off
	ds_read_b128 v[148:151], v140 offset:8288
	v_lshl_add_u64 v[166:167], v[166:167], 0, s[46:47]
	global_load_dwordx4 v[96:99], v[166:167], off
	s_waitcnt lgkmcnt(2)
	v_mfma_f32_32x32x16_bf16 v[48:63], v[80:83], v[72:75], v[32:47]
	s_movk_i32 s2, 0xe8
	s_nop 0
	v_lshl_add_u64 v[186:187], v[186:187], 0, s[50:51]
	global_load_dwordx4 v[100:103], v[186:187], off
	s_waitcnt lgkmcnt(1)
	v_mfma_f32_32x32x16_bf16 v[48:63], v[84:87], v[64:67], v[48:63]
	v_lshl_add_u64 v[166:167], v[166:167], 0, s[46:47]
	global_load_dwordx4 v[104:107], v[166:167], off
	ds_read_b128 v[80:83], v140 offset:8256
	s_nop 0
	v_lshl_add_u64 v[186:187], v[186:187], 0, s[50:51]
	global_load_dwordx4 v[108:111], v[186:187], off
	s_waitcnt lgkmcnt(0)
	v_mfma_f32_32x32x16_bf16 v[48:63], v[80:83], v[68:71], v[48:63]
	ds_read_b128 v[124:127], v141 offset:12800
	ds_read_b128 v[84:87], v141 offset:12832
	ds_read_b128 v[88:91], v141 offset:15360
	ds_read_b128 v[80:83], v141 offset:15392
	s_sub_u32 s100, s29, 10
	s_cmp_lt_u32 s100, 5
	s_cselect_b64 s[100:101], s[98:99], 0
	s_andn2_b64 s[100:101], s[24:25], s[100:101]
	s_and_b64 vcc, exec, s[100:101]
	v_add_u32_e32 v143, s27, v137
	v_mfma_f32_32x32x16_bf16 v[48:63], v[148:151], v[76:79], v[48:63]
	s_cbranch_vccz .LBB0_423
	v_add_u32_e32 v146, 0xfffffe60, v146
	s_movk_i32 s2, 0x4000
	v_cmp_gt_u32_e32 vcc, s2, v146
	v_add_u32_e32 v146, 0xfffffee0, v143
	s_movk_i32 s30, 0x101
	v_cmp_gt_u32_e64 s[2:3], s30, v146
	s_and_b64 s[2:3], vcc, s[2:3]
	v_add_u32_e32 v147, 0xfffffee1, v143
	s_nop 2
	v_cndmask_b32_e64 v146, v237, v48, s[2:3]
	v_cmp_gt_u32_e64 s[2:3], s30, v147
	s_and_b64 s[2:3], vcc, s[2:3]
	v_add_u32_e32 v148, 0xfffffee2, v143
	v_cndmask_b32_e64 v147, v237, v49, s[2:3]
	v_cmp_gt_u32_e64 s[2:3], s30, v148
	s_and_b64 s[2:3], vcc, s[2:3]
	v_add_u32_e32 v149, 0xfffffee3, v143
	v_cndmask_b32_e64 v148, v237, v50, s[2:3]
	v_cmp_gt_u32_e64 s[2:3], s30, v149
	s_and_b64 s[2:3], vcc, s[2:3]
	v_add_u32_e32 v150, 0xfffffee4, v143
	v_cndmask_b32_e64 v149, v237, v51, s[2:3]
	v_cmp_gt_u32_e64 s[2:3], s30, v150
	s_and_b64 s[2:3], vcc, s[2:3]
	v_add_u32_e32 v151, 0xfffffee5, v143
	v_cndmask_b32_e64 v150, v237, v52, s[2:3]
	v_cmp_gt_u32_e64 s[2:3], s30, v151
	s_and_b64 s[2:3], vcc, s[2:3]
	v_add_u32_e32 v156, 0xfffffee6, v143
	v_cndmask_b32_e64 v151, v237, v53, s[2:3]
	v_cmp_gt_u32_e64 s[2:3], s30, v156
	s_and_b64 s[2:3], vcc, s[2:3]
	v_add_u32_e32 v157, 0xfffffee7, v143
	v_cndmask_b32_e64 v156, v237, v54, s[2:3]
	v_cmp_gt_u32_e64 s[2:3], s30, v157
	s_and_b64 s[2:3], vcc, s[2:3]
	v_add_u32_e32 v158, 0xfffffef0, v143
	v_cndmask_b32_e64 v157, v237, v55, s[2:3]
	v_cmp_gt_u32_e64 s[2:3], s30, v158
	s_and_b64 s[2:3], vcc, s[2:3]
	v_add_u32_e32 v159, 0xfffffef1, v143
	v_cndmask_b32_e64 v158, v237, v56, s[2:3]
	v_cmp_gt_u32_e64 s[2:3], s30, v159
	s_and_b64 s[2:3], vcc, s[2:3]
	v_add_u32_e32 v160, 0xfffffef2, v143
	v_cndmask_b32_e64 v159, v237, v57, s[2:3]
	v_cmp_gt_u32_e64 s[2:3], s30, v160
	s_and_b64 s[2:3], vcc, s[2:3]
	v_add_u32_e32 v161, 0xfffffef3, v143
	v_cndmask_b32_e64 v160, v237, v58, s[2:3]
	v_cmp_gt_u32_e64 s[2:3], s30, v161
	s_and_b64 s[2:3], vcc, s[2:3]
	v_add_u32_e32 v162, 0xfffffef4, v143
	v_cndmask_b32_e64 v161, v237, v59, s[2:3]
	v_cmp_gt_u32_e64 s[2:3], s30, v162
	s_and_b64 s[2:3], vcc, s[2:3]
	v_add_u32_e32 v163, 0xfffffef5, v143
	v_cndmask_b32_e64 v162, v237, v60, s[2:3]
	v_cmp_gt_u32_e64 s[2:3], s30, v163
	s_and_b64 s[2:3], vcc, s[2:3]
	v_add_u32_e32 v164, 0xfffffef6, v143
	v_cndmask_b32_e64 v163, v237, v61, s[2:3]
	v_cmp_gt_u32_e64 s[2:3], s30, v164
	s_and_b64 s[2:3], vcc, s[2:3]
	v_add_u32_e32 v165, 0xfffffef7, v143
	v_cndmask_b32_e64 v164, v237, v62, s[2:3]
	v_cmp_gt_u32_e64 s[2:3], s30, v165
	s_and_b64 vcc, vcc, s[2:3]
	v_exp_f32_e32 v146, v146
	v_exp_f32_e32 v147, v147
	v_exp_f32_e32 v148, v148
	v_exp_f32_e32 v149, v149
	v_exp_f32_e32 v150, v150
	v_exp_f32_e32 v151, v151
	v_exp_f32_e32 v156, v156
	v_exp_f32_e32 v157, v157
	v_exp_f32_e32 v158, v158
	v_exp_f32_e32 v159, v159
	v_exp_f32_e32 v160, v160
	v_exp_f32_e32 v161, v161
	v_exp_f32_e32 v162, v162
	v_exp_f32_e32 v163, v163
	v_exp_f32_e32 v164, v164
	v_cndmask_b32_e32 v63, v237, v63, vcc
	s_cbranch_execz .LBB0_424
	s_branch .LBB0_425

; DI void frag64_load(Frag64& f, const bf16_t* P, const bf16_t* vt, int b, int u, int kcol, int lane) {
; #pragma unroll
;   for (int i = 0; i < 4; ++i) {
;     f.k[i] = *(const u32x4*)(P + (size_t)rowOfU(b, u + (lane >> 3) + 8 * i) * NP + kcol + (lane & 7) * 8);
;     f.v[i] = *(const u32x4*)(vt + (size_t)((lane >> 2) + 16 * i) * UA + u + (lane & 3) * 8);
;   }
; }
; template <int MODE>
; DI void attn64_wave(const Params& p, int layer, int b, int hq, int qrow0, int t0, const float* rpb_lds, unsigned char* wlds) {
;     ...
;   auto compute_tile = [&](const Frag64& f, int t) {
; #pragma unroll
;     for (int i = 0; i < 4; ++i) {
;       *(u32x4*)(Kw + ((lane >> 3) + 8 * i) * LDS_STRIDE + (lane & 7) * 16) = f.k[i];
;       *(u32x4*)(Vw + ((lane >> 2) + 16 * i) * W64_VSTR + (lane & 3) * 16) = f.v[i];
;     }
;     bf16x8 kf[4], vf[2][2];
; #pragma unroll
;     for (int ks = 0; ks < 4; ++ks) kf[ks] = __builtin_bit_cast(bf16x8, *(const u32x4*)(Kw + pr * LDS_STRIDE + (16 * ks + 8 * hh) * 2));
; #pragma unroll
;     for (int dh = 0; dh < 2; ++dh)
; #pragma unroll
;       for (int s2 = 0; s2 < 2; ++s2) vf[dh][s2] = __builtin_bit_cast(bf16x8, *(const u32x4*)(Vw + (32 * dh + qi) * W64_VSTR + (16 * s2 + 8 * hh) * 2));
;     f32x16 s;
; #pragma unroll
;     for (int i = 0; i < 16; ++i) s[i] = negM2;
; #pragma unroll
;     for (int ks = 0; ks < 4; ++ks) s = MFMA32(kf[ks], qf[ks], s);
;     float pe[16];
;     if (t < 8) {
; #pragma unroll
;       for (int i = 0; i < 16; ++i) pe[i] = fexp2(s[i]);
;     } else if (MODE == 0) {
;       const int kr = rs + ((t - 8) >> 1), hf = (t - 8) & 1;
;       const float* rrow = rpb + (kr - r + 7) * 31 + 15 - c;
; #pragma unroll
;       for (int i = 0; i < 16; ++i) {
;         const int kc = hf * 32 + 16 * (i >> 3) + 8 * hh + (i & 7);
;         const bool valid = (kc >= ws) && (kc < ws + 16);
;         const int kcc = min(max(kc, ws), ws + 15);
;         pe[i] = fexp2(valid ? s[i] + rrow[kcc] : -1e30f);
;       }
;     } else {
;       const int jt = t - 8, kt0 = t0 - 128 + 32 * jt;
;       const bool tile_ok = (jt < 9) && (kt0 >= 0) && (kt0 < SEQ);
; #pragma unroll
;       for (int i = 0; i < 16; ++i) {
;         const int dd = kt0 + 16 * (i >> 3) + 8 * hh + (i & 7) - qt;
;         pe[i] = fexp2((tile_ok && dd <= 128 && dd >= -128) ? s[i] : -1e30f);
;       }
;     }
;     sum16_nopk(ls, pe);
; #pragma unroll
.LBB0_425:
	s_add_i32 s30, s29, 2
	s_cmp_gt_u32 s29, 15
	s_cselect_b64 s[2:3], -1, 0
	s_cmp_lt_u32 s29, 16
	s_cselect_b32 s31, s30, 0
	s_cmp_lt_u32 s31, 8
	v_cvt_pk_bf16_f32 v48, v146, v147
	v_cvt_pk_bf16_f32 v49, v148, v149
	v_cvt_pk_bf16_f32 v50, v150, v151
	v_cvt_pk_bf16_f32 v51, v156, v157
	s_cselect_b64 vcc, -1, 0
	s_lshl_b32 s31, s31, 5
	s_waitcnt lgkmcnt(3)
	v_mfma_f32_32x32x16_bf16 v[16:31], v[124:127], v[48:51], v[16:31]
	v_exp_f32_e32 v55, v63
	s_nop 0
	v_add_f32 v135, v146, v135
	v_add_f32 v135, v147, v135
	v_add_f32 v135, v148, v135
	v_add_f32 v135, v149, v135
	v_add_f32 v135, v150, v135
	v_add_f32 v135, v151, v135
	v_add_f32 v135, v156, v135
	v_add_f32 v135, v157, v135
	v_add_f32 v135, v158, v135
	v_add_f32 v135, v159, v135
	v_add_f32 v135, v160, v135
	v_add_f32 v135, v161, v135
	v_add_f32 v135, v162, v135
	v_add_f32 v135, v163, v135
	v_add_f32 v135, v164, v135
	v_add_f32 v135, v55, v135
	v_mov_b32_e32 v127, s28
	v_mov_b32_e32 v146, s22
	v_cvt_pk_bf16_f32 v52, v158, v159
	v_cvt_pk_bf16_f32 v53, v160, v161
	v_cvt_pk_bf16_f32 v54, v162, v163
	s_waitcnt lgkmcnt(1)
	v_mfma_f32_32x32x16_bf16 v[0:15], v[88:91], v[48:51], v[0:15]
	v_add_u32_e32 v48, s31, v136
	v_med3_i32 v48, v48, 0, v236
	v_add_u32_e32 v48, 0x100, v48
	v_mov_b32_e32 v49, s31
	v_cndmask_b32_e32 v192, v48, v49, vcc
	v_add_u32_e32 v126, v192, v134
	s_movk_i32 s31, 0x100
	v_cmp_gt_u32_e32 vcc, s31, v126
	s_movk_i32 s31, 0xf8
	v_cvt_pk_bf16_f32 v55, v164, v55
	v_cndmask_b32_e32 v48, v127, v146, vcc
	v_add_u32_e32 v48, v48, v126
	v_mad_i64_i32 v[166:167], s[42:43], v48, s20, v[130:131]
	v_mfma_f32_32x32x16_bf16 v[16:31], v[84:87], v[52:55], v[16:31]
	global_load_dwordx4 v[84:87], v[166:167], off
	v_lshl_add_u64 v[124:125], v[192:193], 1, v[128:129]
	v_lshl_add_u64 v[166:167], v[166:167], 0, s[46:47]
	global_load_dwordx4 v[88:91], v[166:167], off
	s_waitcnt lgkmcnt(0)
	v_mfma_f32_32x32x16_bf16 v[0:15], v[80:83], v[52:55], v[0:15]
	global_load_dwordx4 v[80:83], v[124:125], off
	s_waitcnt vmcnt(9)
	ds_write_b128 v138, v[112:115] offset:8192
	ds_write_b128 v139, v[116:119] offset:12800
	s_waitcnt vmcnt(8)
	ds_write_b128 v138, v[120:123] offset:9344
	s_waitcnt vmcnt(7)
	ds_write_b128 v139, v[92:95] offset:14080
	s_waitcnt vmcnt(6)
	ds_write_b128 v138, v[96:99] offset:10496
	s_waitcnt vmcnt(5)
	ds_write_b128 v139, v[100:103] offset:15360
	s_waitcnt vmcnt(4)
	ds_write_b128 v138, v[104:107] offset:11648
	s_waitcnt vmcnt(3)
	ds_write_b128 v139, v[108:111] offset:16640
	ds_read_b128 v[100:103], v140 offset:8192
	ds_read_b128 v[104:107], v140 offset:8224
	s_movk_i32 s31, 0xf0
	s_nop 0
	v_lshl_add_u64 v[186:187], v[124:125], 0, s[50:51]
	global_load_dwordx4 v[92:95], v[186:187], off
	s_movk_i32 s31, 0xe8
	v_lshl_add_u64 v[166:167], v[166:167], 0, s[46:47]
	global_load_dwordx4 v[96:99], v[166:167], off
	s_waitcnt lgkmcnt(1)
	v_mfma_f32_32x32x16_bf16 v[48:63], v[100:103], v[72:75], v[32:47]
	s_nop 1
	v_lshl_add_u64 v[186:187], v[186:187], 0, s[50:51]
	global_load_dwordx4 v[100:103], v[186:187], off
	s_waitcnt lgkmcnt(0)
	v_mfma_f32_32x32x16_bf16 v[48:63], v[104:107], v[64:67], v[48:63]
	ds_read_b128 v[108:111], v140 offset:8256
	ds_read_b128 v[146:149], v140 offset:8288
	v_lshl_add_u64 v[166:167], v[166:167], 0, s[46:47]
	global_load_dwordx4 v[104:107], v[166:167], off
	s_nop 0
	v_lshl_add_u64 v[186:187], v[186:187], 0, s[50:51]
	s_waitcnt lgkmcnt(1)
	v_mfma_f32_32x32x16_bf16 v[48:63], v[108:111], v[68:71], v[48:63]
	global_load_dwordx4 v[108:111], v[186:187], off
	ds_read_b128 v[120:123], v141 offset:12800
	ds_read_b128 v[112:115], v141 offset:12832
	ds_read_b128 v[124:127], v141 offset:15360
	ds_read_b128 v[116:119], v141 offset:15392
	s_sub_u32 s100, s29, 8
	s_cmp_lt_u32 s100, 7
	s_cselect_b64 s[100:101], s[98:99], 0
	s_andn2_b64 s[100:101], s[24:25], s[100:101]
	s_and_b64 vcc, exec, s[100:101]
	s_waitcnt lgkmcnt(4)
	v_mfma_f32_32x32x16_bf16 v[48:63], v[146:149], v[76:79], v[48:63]
	s_cbranch_vccz .LBB0_427
	s_add_i32 s24, s29, 1
	s_cmp_lt_u32 s24, 17
	s_movk_i32 s29, 0x4000
	s_cselect_b64 s[24:25], -1, 0
	v_cmp_gt_u32_e32 vcc, s29, v142
	v_add_u32_e32 v142, 0xffffff00, v143
	s_movk_i32 s29, 0x101
	s_and_b64 s[24:25], s[24:25], vcc
	v_cmp_gt_u32_e32 vcc, s29, v142
	s_and_b64 vcc, s[24:25], vcc
	v_add_u32_e32 v146, 0xffffff01, v143
	v_cndmask_b32_e32 v142, v237, v48, vcc
	v_cmp_gt_u32_e32 vcc, s29, v146
	s_and_b64 vcc, s[24:25], vcc
	v_add_u32_e32 v147, 0xffffff02, v143
	v_cndmask_b32_e32 v146, v237, v49, vcc
	v_cmp_gt_u32_e32 vcc, s29, v147
	s_and_b64 vcc, s[24:25], vcc
	v_add_u32_e32 v148, 0xffffff03, v143
	v_cndmask_b32_e32 v147, v237, v50, vcc
	v_cmp_gt_u32_e32 vcc, s29, v148
	s_and_b64 vcc, s[24:25], vcc
	v_add_u32_e32 v149, 0xffffff04, v143
	v_cndmask_b32_e32 v148, v237, v51, vcc
	v_cmp_gt_u32_e32 vcc, s29, v149
	s_and_b64 vcc, s[24:25], vcc
	v_add_u32_e32 v150, 0xffffff05, v143
	v_cndmask_b32_e32 v149, v237, v52, vcc
	v_cmp_gt_u32_e32 vcc, s29, v150
	s_and_b64 vcc, s[24:25], vcc
	v_add_u32_e32 v151, 0xffffff06, v143
	v_cndmask_b32_e32 v150, v237, v53, vcc
	v_cmp_gt_u32_e32 vcc, s29, v151
	s_and_b64 vcc, s[24:25], vcc
	v_add_u32_e32 v156, 0xffffff07, v143
	v_cndmask_b32_e32 v151, v237, v54, vcc
	v_cmp_gt_u32_e32 vcc, s29, v156
	s_and_b64 vcc, s[24:25], vcc
	v_add_u32_e32 v158, 0xffffff11, v143
	v_cndmask_b32_e32 v156, v237, v55, vcc
	v_exp_f32_e32 v157, v156
	v_add_u32_e32 v156, 0xffffff10, v143
	v_cmp_gt_u32_e32 vcc, s29, v156
	s_and_b64 vcc, s[24:25], vcc
	v_add_u32_e32 v159, 0xffffff12, v143
	v_cndmask_b32_e32 v156, v237, v56, vcc
	v_cmp_gt_u32_e32 vcc, s29, v158
	s_and_b64 vcc, s[24:25], vcc
	v_add_u32_e32 v160, 0xffffff13, v143
	v_cndmask_b32_e32 v158, v237, v57, vcc
	v_cmp_gt_u32_e32 vcc, s29, v159
	s_and_b64 vcc, s[24:25], vcc
	v_add_u32_e32 v161, 0xffffff14, v143
	v_cndmask_b32_e32 v159, v237, v58, vcc
	v_cmp_gt_u32_e32 vcc, s29, v160
	s_and_b64 vcc, s[24:25], vcc
	v_add_u32_e32 v162, 0xffffff15, v143
	v_cndmask_b32_e32 v160, v237, v59, vcc
	v_cmp_gt_u32_e32 vcc, s29, v161
	s_and_b64 vcc, s[24:25], vcc
	v_add_u32_e32 v163, 0xffffff16, v143
	v_cndmask_b32_e32 v161, v237, v60, vcc
	v_cmp_gt_u32_e32 vcc, s29, v162
	s_and_b64 vcc, s[24:25], vcc
	v_add_u32_e32 v143, 0xffffff17, v143
	v_cndmask_b32_e32 v162, v237, v61, vcc
	v_cmp_gt_u32_e32 vcc, s29, v163
	s_and_b64 vcc, s[24:25], vcc
	v_exp_f32_e32 v142, v142
	v_cndmask_b32_e32 v163, v237, v62, vcc
	v_cmp_gt_u32_e32 vcc, s29, v143
	s_and_b64 vcc, s[24:25], vcc
	v_exp_f32_e32 v146, v146
	v_exp_f32_e32 v147, v147
	v_exp_f32_e32 v148, v148
	v_exp_f32_e32 v149, v149
	v_exp_f32_e32 v150, v150
	v_exp_f32_e32 v151, v151
	v_exp_f32_e32 v156, v156
	v_exp_f32_e32 v158, v158
	v_exp_f32_e32 v159, v159
	v_exp_f32_e32 v160, v160
	v_exp_f32_e32 v161, v161
	v_exp_f32_e32 v162, v162
	v_exp_f32_e32 v163, v163
	v_cndmask_b32_e32 v63, v237, v63, vcc
	s_cbranch_execnz .LBB0_420
	s_branch .LBB0_428
